# gemm_phase UQ/UKV: operand loads of all K-steps issued at the top of the tile (extra landing registers), staging waits re-derived
# baseline (speedup 1.0000x reference)
.LBB0_1296:
	s_mul_hi_i32 s0, s4, 0x55555556
	s_lshr_b32 s1, s0, 31
	s_add_i32 s0, s0, s1
	s_mul_i32 s1, s0, -3
	s_lshl_b32 s2, s0, 7
	s_add_i32 s1, s1, s4
	s_ashr_i32 s3, s2, 31
	s_lshl_b32 s0, s1, 7
	s_lshl_b64 s[6:7], s[2:3], 12
	s_ashr_i32 s1, s0, 31
	v_lshl_add_u64 v[6:7], v[80:81], 0, s[6:7]
	s_lshl_b64 s[6:7], s[0:1], 9
	v_lshl_add_u64 v[0:1], v[6:7], 0, v[84:85]
	v_lshl_add_u64 v[4:5], v[6:7], 0, v[88:89]
	v_lshl_add_u64 v[2:3], v[6:7], 0, v[92:93]
	v_lshl_add_u64 v[10:11], v[6:7], 0, v[96:97]
	v_lshl_add_u64 v[6:7], v[82:83], 0, s[6:7]
	v_lshl_add_u64 v[14:15], v[6:7], 0, v[86:87]
	global_load_dwordx4 v[16:19], v[0:1], off offset:1568
	global_load_dwordx4 v[20:23], v[4:5], off offset:1568
	global_load_dwordx4 v[24:27], v[2:3], off offset:1568
	global_load_dwordx4 v[28:31], v[10:11], off offset:1568
	v_lshl_add_u64 v[12:13], v[6:7], 0, v[90:91]
	s_waitcnt vmcnt(4)
	v_lshl_add_u64 v[8:9], v[6:7], 0, v[94:95]
	v_lshl_add_u64 v[6:7], v[6:7], 0, v[98:99]
	global_load_dwordx4 v[32:35], v[14:15], off
	global_load_dwordx4 v[36:39], v[12:13], off
	global_load_dwordx4 v[40:43], v[8:9], off
	global_load_dwordx4 v[44:47], v[6:7], off
	global_load_dwordx4 v[208:211], v[0:1], off offset:1696
	global_load_dwordx4 v[212:215], v[4:5], off offset:1696
	global_load_dwordx4 v[216:219], v[2:3], off offset:1696
	global_load_dwordx4 v[220:223], v[10:11], off offset:1696
	global_load_dwordx4 v[224:227], v[14:15], off offset:128
	global_load_dwordx4 v[228:231], v[12:13], off offset:128
	global_load_dwordx4 v[232:235], v[8:9], off offset:128
	global_load_dwordx4 v[236:239], v[6:7], off offset:128
	global_load_dwordx4 v[240:243], v[0:1], off offset:1824
	global_load_dwordx4 v[244:247], v[4:5], off offset:1824
	global_load_dwordx4 v[142:145], v[2:3], off offset:1824
	global_load_dwordx4 v[146:149], v[10:11], off offset:1824
	global_load_dwordx4 v[150:153], v[14:15], off offset:256
	global_load_dwordx4 v[154:157], v[12:13], off offset:256
	global_load_dwordx4 v[158:161], v[8:9], off offset:256
	s_barrier
	s_mov_b32 s1, s5
	s_waitcnt vmcnt(22)
	ds_write_b128 v104, v[16:19]
	s_waitcnt vmcnt(21)
	ds_write_b128 v105, v[20:23]
	s_waitcnt vmcnt(20)
	ds_write_b128 v106, v[24:27]
	s_waitcnt vmcnt(19)
	ds_write_b128 v107, v[28:31]
	s_waitcnt vmcnt(18)
	ds_write_b128 v104, v[32:35] offset:18432
	s_waitcnt vmcnt(17)
	ds_write_b128 v105, v[36:39] offset:18432
	s_waitcnt vmcnt(16)
	ds_write_b128 v106, v[40:43] offset:18432
	s_waitcnt vmcnt(15)
	ds_write_b128 v107, v[44:47] offset:18432
	s_waitcnt lgkmcnt(0)
	s_barrier
	ds_read_b128 v[16:19], v109 offset:18432
	ds_read_b128 v[20:23], v108
	ds_read_b128 v[28:31], v109 offset:20736
	ds_read_b128 v[118:121], v109 offset:20800
	ds_read_b128 v[36:39], v109 offset:23040
	ds_read_b128 v[122:125], v109 offset:23104
	ds_read_b128 v[44:47], v109 offset:25344
	ds_read_b128 v[134:137], v109 offset:25408
	ds_read_b128 v[48:51], v108 offset:2304
	ds_read_b128 v[64:67], v108 offset:4608
	ds_read_b128 v[110:113], v108 offset:6912
	ds_read_b128 v[114:117], v109 offset:18496
	s_waitcnt lgkmcnt(10)
	v_mfma_f32_16x16x32_bf16 v[24:27], v[16:19], v[20:23], 0
	ds_read_b128 v[138:141], v108 offset:6976
	s_waitcnt lgkmcnt(10)
	v_mfma_f32_16x16x32_bf16 v[32:35], v[28:31], v[20:23], 0
	s_waitcnt lgkmcnt(8)
	v_mfma_f32_16x16x32_bf16 v[40:43], v[36:39], v[20:23], 0
	s_waitcnt lgkmcnt(6)
	v_mfma_f32_16x16x32_bf16 v[20:23], v[44:47], v[20:23], 0
	s_waitcnt lgkmcnt(4)
	v_mfma_f32_16x16x32_bf16 v[52:55], v[16:19], v[48:51], 0
	v_mfma_f32_16x16x32_bf16 v[56:59], v[28:31], v[48:51], 0
	v_mfma_f32_16x16x32_bf16 v[60:63], v[36:39], v[48:51], 0
	v_mfma_f32_16x16x32_bf16 v[48:51], v[44:47], v[48:51], 0
	s_waitcnt lgkmcnt(3)
	v_mfma_f32_16x16x32_bf16 v[68:71], v[16:19], v[64:67], 0
	v_mfma_f32_16x16x32_bf16 v[72:75], v[28:31], v[64:67], 0
	v_mfma_f32_16x16x32_bf16 v[76:79], v[36:39], v[64:67], 0
	v_mfma_f32_16x16x32_bf16 v[64:67], v[44:47], v[64:67], 0
	s_waitcnt lgkmcnt(2)
	v_mfma_f32_16x16x32_bf16 v[16:19], v[16:19], v[110:113], 0
	v_mfma_f32_16x16x32_bf16 v[28:31], v[28:31], v[110:113], 0
	v_mfma_f32_16x16x32_bf16 v[36:39], v[36:39], v[110:113], 0
	v_mfma_f32_16x16x32_bf16 v[44:47], v[44:47], v[110:113], 0
	ds_read_b128 v[110:113], v108 offset:64
	s_waitcnt lgkmcnt(0)
	v_mfma_f32_16x16x32_bf16 v[24:27], v[114:117], v[110:113], v[24:27]
	v_mfma_f32_16x16x32_bf16 v[32:35], v[118:121], v[110:113], v[32:35]
	v_mfma_f32_16x16x32_bf16 v[40:43], v[122:125], v[110:113], v[40:43]
	v_mfma_f32_16x16x32_bf16 v[20:23], v[134:137], v[110:113], v[20:23]
	ds_read_b128 v[110:113], v108 offset:2368
	s_waitcnt lgkmcnt(0)
	v_mfma_f32_16x16x32_bf16 v[52:55], v[114:117], v[110:113], v[52:55]
	v_mfma_f32_16x16x32_bf16 v[56:59], v[118:121], v[110:113], v[56:59]
	v_mfma_f32_16x16x32_bf16 v[60:63], v[122:125], v[110:113], v[60:63]
	v_mfma_f32_16x16x32_bf16 v[48:51], v[134:137], v[110:113], v[48:51]
	ds_read_b128 v[110:113], v108 offset:4672
	s_waitcnt lgkmcnt(0)
	v_mfma_f32_16x16x32_bf16 v[68:71], v[114:117], v[110:113], v[68:71]
	v_mfma_f32_16x16x32_bf16 v[72:75], v[118:121], v[110:113], v[72:75]
	v_mfma_f32_16x16x32_bf16 v[76:79], v[122:125], v[110:113], v[76:79]
	v_mfma_f32_16x16x32_bf16 v[64:67], v[134:137], v[110:113], v[64:67]
	v_mfma_f32_16x16x32_bf16 v[16:19], v[114:117], v[138:141], v[16:19]
	v_mfma_f32_16x16x32_bf16 v[28:31], v[118:121], v[138:141], v[28:31]
	s_barrier
	v_mfma_f32_16x16x32_bf16 v[36:39], v[122:125], v[138:141], v[36:39]
	s_waitcnt vmcnt(14)
	ds_write_b128 v104, v[208:211]
	s_waitcnt vmcnt(13)
	ds_write_b128 v105, v[212:215]
	s_waitcnt vmcnt(12)
	ds_write_b128 v106, v[216:219]
	s_waitcnt vmcnt(11)
	ds_write_b128 v107, v[220:223]
	s_waitcnt vmcnt(10)
	ds_write_b128 v104, v[224:227] offset:18432
	s_waitcnt vmcnt(9)
	ds_write_b128 v105, v[228:231] offset:18432
	s_waitcnt vmcnt(8)
	ds_write_b128 v106, v[232:235] offset:18432
	s_waitcnt vmcnt(7)
	ds_write_b128 v107, v[236:239] offset:18432
	v_mfma_f32_16x16x32_bf16 v[44:47], v[134:137], v[138:141], v[44:47]
	s_waitcnt lgkmcnt(0)
	global_load_dwordx4 v[208:211], v[6:7], off offset:256
	global_load_dwordx4 v[212:215], v[0:1], off offset:1952
	global_load_dwordx4 v[216:219], v[4:5], off offset:1952
	global_load_dwordx4 v[220:223], v[2:3], off offset:1952
	global_load_dwordx4 v[224:227], v[10:11], off offset:1952
	global_load_dwordx4 v[228:231], v[14:15], off offset:384
	global_load_dwordx4 v[232:235], v[12:13], off offset:384
	global_load_dwordx4 v[236:239], v[8:9], off offset:384
	s_barrier
	ds_read_b128 v[110:113], v109 offset:18432
	ds_read_b128 v[114:117], v108
	ds_read_b128 v[118:121], v109 offset:20736
	ds_read_b128 v[122:125], v109 offset:23040
	ds_read_b128 v[134:137], v109 offset:25344
	s_waitcnt lgkmcnt(3)
	v_mfma_f32_16x16x32_bf16 v[24:27], v[110:113], v[114:117], v[24:27]
	ds_read_b128 v[138:141], v108 offset:6976
	s_waitcnt lgkmcnt(3)
	v_mfma_f32_16x16x32_bf16 v[32:35], v[118:121], v[114:117], v[32:35]
	s_waitcnt lgkmcnt(2)
	v_mfma_f32_16x16x32_bf16 v[40:43], v[122:125], v[114:117], v[40:43]
	s_waitcnt lgkmcnt(1)
	v_mfma_f32_16x16x32_bf16 v[20:23], v[134:137], v[114:117], v[20:23]
	ds_read_b128 v[114:117], v108 offset:2304
	s_waitcnt lgkmcnt(0)
	v_mfma_f32_16x16x32_bf16 v[52:55], v[110:113], v[114:117], v[52:55]
	v_mfma_f32_16x16x32_bf16 v[56:59], v[118:121], v[114:117], v[56:59]
	v_mfma_f32_16x16x32_bf16 v[60:63], v[122:125], v[114:117], v[60:63]
	v_mfma_f32_16x16x32_bf16 v[48:51], v[134:137], v[114:117], v[48:51]
	ds_read_b128 v[114:117], v108 offset:4608
	s_waitcnt lgkmcnt(0)
	v_mfma_f32_16x16x32_bf16 v[68:71], v[110:113], v[114:117], v[68:71]
	v_mfma_f32_16x16x32_bf16 v[72:75], v[118:121], v[114:117], v[72:75]
	v_mfma_f32_16x16x32_bf16 v[76:79], v[122:125], v[114:117], v[76:79]
	v_mfma_f32_16x16x32_bf16 v[64:67], v[134:137], v[114:117], v[64:67]
	ds_read_b128 v[114:117], v108 offset:6912
	s_waitcnt lgkmcnt(0)
	v_mfma_f32_16x16x32_bf16 v[16:19], v[110:113], v[114:117], v[16:19]
	ds_read_b128 v[110:113], v109 offset:18496
	v_mfma_f32_16x16x32_bf16 v[28:31], v[118:121], v[114:117], v[28:31]
	ds_read_b128 v[118:121], v109 offset:20800
	v_mfma_f32_16x16x32_bf16 v[36:39], v[122:125], v[114:117], v[36:39]
	ds_read_b128 v[122:125], v109 offset:23104
	v_mfma_f32_16x16x32_bf16 v[44:47], v[134:137], v[114:117], v[44:47]
	ds_read_b128 v[134:137], v109 offset:25408
	ds_read_b128 v[114:117], v108 offset:64
	s_waitcnt lgkmcnt(0)
	v_mfma_f32_16x16x32_bf16 v[24:27], v[110:113], v[114:117], v[24:27]
	v_mfma_f32_16x16x32_bf16 v[32:35], v[118:121], v[114:117], v[32:35]
	v_mfma_f32_16x16x32_bf16 v[40:43], v[122:125], v[114:117], v[40:43]
	v_mfma_f32_16x16x32_bf16 v[20:23], v[134:137], v[114:117], v[20:23]
	ds_read_b128 v[114:117], v108 offset:2368
	s_waitcnt lgkmcnt(0)
	v_mfma_f32_16x16x32_bf16 v[52:55], v[110:113], v[114:117], v[52:55]
	v_mfma_f32_16x16x32_bf16 v[56:59], v[118:121], v[114:117], v[56:59]
	v_mfma_f32_16x16x32_bf16 v[60:63], v[122:125], v[114:117], v[60:63]
	v_mfma_f32_16x16x32_bf16 v[48:51], v[134:137], v[114:117], v[48:51]
	ds_read_b128 v[114:117], v108 offset:4672
	s_waitcnt lgkmcnt(0)
	v_mfma_f32_16x16x32_bf16 v[68:71], v[110:113], v[114:117], v[68:71]
	v_mfma_f32_16x16x32_bf16 v[72:75], v[118:121], v[114:117], v[72:75]
	v_mfma_f32_16x16x32_bf16 v[76:79], v[122:125], v[114:117], v[76:79]
	v_mfma_f32_16x16x32_bf16 v[64:67], v[134:137], v[114:117], v[64:67]
	v_mfma_f32_16x16x32_bf16 v[16:19], v[110:113], v[138:141], v[16:19]
	v_mfma_f32_16x16x32_bf16 v[28:31], v[118:121], v[138:141], v[28:31]
	s_barrier
	v_mfma_f32_16x16x32_bf16 v[36:39], v[122:125], v[138:141], v[36:39]
	s_waitcnt vmcnt(14)
	ds_write_b128 v104, v[240:243]
	s_waitcnt vmcnt(13)
	ds_write_b128 v105, v[244:247]
	s_waitcnt vmcnt(12)
	ds_write_b128 v106, v[142:145]
	s_waitcnt vmcnt(11)
	ds_write_b128 v107, v[146:149]
	s_waitcnt vmcnt(10)
	ds_write_b128 v104, v[150:153] offset:18432
	s_waitcnt vmcnt(9)
	ds_write_b128 v105, v[154:157] offset:18432
	s_waitcnt vmcnt(8)
	ds_write_b128 v106, v[158:161] offset:18432
	s_waitcnt vmcnt(7)
	ds_write_b128 v107, v[208:211] offset:18432
	v_mfma_f32_16x16x32_bf16 v[44:47], v[134:137], v[138:141], v[44:47]
	s_waitcnt lgkmcnt(0)
	global_load_dwordx4 v[240:243], v[6:7], off offset:384
	s_barrier
	ds_read_b128 v[110:113], v109 offset:18432
	ds_read_b128 v[114:117], v108
	ds_read_b128 v[118:121], v109 offset:20736
	ds_read_b128 v[122:125], v109 offset:23040
	ds_read_b128 v[134:137], v109 offset:25344
	s_waitcnt lgkmcnt(3)
	v_mfma_f32_16x16x32_bf16 v[24:27], v[110:113], v[114:117], v[24:27]
	s_waitcnt lgkmcnt(2)
	v_mfma_f32_16x16x32_bf16 v[32:35], v[118:121], v[114:117], v[32:35]
	s_waitcnt lgkmcnt(1)
	v_mfma_f32_16x16x32_bf16 v[40:43], v[122:125], v[114:117], v[40:43]
	s_waitcnt lgkmcnt(0)
	v_mfma_f32_16x16x32_bf16 v[20:23], v[134:137], v[114:117], v[20:23]
	ds_read_b128 v[114:117], v108 offset:2304
	s_waitcnt lgkmcnt(0)
	v_mfma_f32_16x16x32_bf16 v[52:55], v[110:113], v[114:117], v[52:55]
	v_mfma_f32_16x16x32_bf16 v[56:59], v[118:121], v[114:117], v[56:59]
	v_mfma_f32_16x16x32_bf16 v[60:63], v[122:125], v[114:117], v[60:63]
	v_mfma_f32_16x16x32_bf16 v[48:51], v[134:137], v[114:117], v[48:51]
	ds_read_b128 v[114:117], v108 offset:4608
	s_waitcnt lgkmcnt(0)
	v_mfma_f32_16x16x32_bf16 v[68:71], v[110:113], v[114:117], v[68:71]
	v_mfma_f32_16x16x32_bf16 v[72:75], v[118:121], v[114:117], v[72:75]
	v_mfma_f32_16x16x32_bf16 v[76:79], v[122:125], v[114:117], v[76:79]
	v_mfma_f32_16x16x32_bf16 v[64:67], v[134:137], v[114:117], v[64:67]
	ds_read_b128 v[114:117], v108 offset:6912
	s_waitcnt lgkmcnt(0)
	v_mfma_f32_16x16x32_bf16 v[16:19], v[110:113], v[114:117], v[16:19]
	ds_read_b128 v[110:113], v109 offset:18496
	v_mfma_f32_16x16x32_bf16 v[28:31], v[118:121], v[114:117], v[28:31]
	ds_read_b128 v[118:121], v109 offset:20800
	v_mfma_f32_16x16x32_bf16 v[36:39], v[122:125], v[114:117], v[36:39]
	ds_read_b128 v[122:125], v109 offset:23104
	v_mfma_f32_16x16x32_bf16 v[44:47], v[134:137], v[114:117], v[44:47]
	ds_read_b128 v[134:137], v109 offset:25408
	ds_read_b128 v[114:117], v108 offset:64
	s_waitcnt lgkmcnt(0)
	v_mfma_f32_16x16x32_bf16 v[24:27], v[110:113], v[114:117], v[24:27]
	v_mfma_f32_16x16x32_bf16 v[32:35], v[118:121], v[114:117], v[32:35]
	v_mfma_f32_16x16x32_bf16 v[40:43], v[122:125], v[114:117], v[40:43]
	v_mfma_f32_16x16x32_bf16 v[20:23], v[134:137], v[114:117], v[20:23]
	ds_read_b128 v[114:117], v108 offset:2368
	s_waitcnt lgkmcnt(0)
	v_mfma_f32_16x16x32_bf16 v[52:55], v[110:113], v[114:117], v[52:55]
	v_mfma_f32_16x16x32_bf16 v[56:59], v[118:121], v[114:117], v[56:59]
	v_mfma_f32_16x16x32_bf16 v[60:63], v[122:125], v[114:117], v[60:63]
	v_mfma_f32_16x16x32_bf16 v[48:51], v[134:137], v[114:117], v[48:51]
	ds_read_b128 v[114:117], v108 offset:4672
	s_waitcnt lgkmcnt(0)
	v_mfma_f32_16x16x32_bf16 v[138:141], v[122:125], v[114:117], v[76:79]
	s_nop 2
	ds_read_b128 v[76:79], v108 offset:6976
	v_mfma_f32_16x16x32_bf16 v[68:71], v[110:113], v[114:117], v[68:71]
	v_mfma_f32_16x16x32_bf16 v[72:75], v[118:121], v[114:117], v[72:75]
	v_mfma_f32_16x16x32_bf16 v[64:67], v[134:137], v[114:117], v[64:67]
	s_waitcnt lgkmcnt(0)
	v_mfma_f32_16x16x32_bf16 v[14:17], v[110:113], v[76:79], v[16:19]
	s_nop 0
	s_nop 0
	s_nop 0
	s_barrier
	s_waitcnt vmcnt(7)
	ds_write_b128 v104, v[212:215]
	s_waitcnt vmcnt(6)
	ds_write_b128 v105, v[216:219]
	s_waitcnt vmcnt(5)
	ds_write_b128 v106, v[220:223]
	s_waitcnt vmcnt(4)
	ds_write_b128 v107, v[224:227]
	s_waitcnt vmcnt(3)
	ds_write_b128 v104, v[228:231] offset:18432
	s_waitcnt vmcnt(2)
	ds_write_b128 v105, v[232:235] offset:18432
	s_waitcnt vmcnt(1)
	ds_write_b128 v106, v[236:239] offset:18432
	s_waitcnt vmcnt(0)
	ds_write_b128 v107, v[240:243] offset:18432
	s_waitcnt lgkmcnt(0)
	s_barrier
	ds_read_b128 v[0:3], v109 offset:18432
	ds_read_b128 v[4:7], v108
	s_waitcnt lgkmcnt(0)
	v_mfma_f32_16x16x32_bf16 v[110:113], v[0:3], v[4:7], v[24:27]
	s_nop 2
	ds_read_b128 v[24:27], v109 offset:20736
	s_waitcnt lgkmcnt(0)
	v_mfma_f32_16x16x32_bf16 v[114:117], v[24:27], v[4:7], v[32:35]
	s_nop 2
	ds_read_b128 v[32:35], v109 offset:23040
	v_mfma_f32_16x16x32_bf16 v[28:31], v[118:121], v[76:79], v[28:31]
	s_waitcnt lgkmcnt(0)
	v_mfma_f32_16x16x32_bf16 v[118:121], v[32:35], v[4:7], v[40:43]
	s_nop 2
	ds_read_b128 v[40:43], v109 offset:25344
	v_mfma_f32_16x16x32_bf16 v[36:39], v[122:125], v[76:79], v[36:39]
	s_waitcnt lgkmcnt(0)
	v_mfma_f32_16x16x32_bf16 v[122:125], v[40:43], v[4:7], v[20:23]
	ds_read_b128 v[4:7], v108 offset:2304
	s_nop 1
	ds_read_b128 v[18:21], v108 offset:6912
	v_mfma_f32_16x16x32_bf16 v[44:47], v[134:137], v[76:79], v[44:47]
	s_waitcnt lgkmcnt(1)
	v_mfma_f32_16x16x32_bf16 v[134:137], v[0:3], v[4:7], v[52:55]
	v_mfma_f32_16x16x32_bf16 v[142:145], v[24:27], v[4:7], v[56:59]
	v_mfma_f32_16x16x32_bf16 v[60:63], v[32:35], v[4:7], v[60:63]
	s_nop 1
	ds_read_b128 v[56:59], v109 offset:25408
	v_mfma_f32_16x16x32_bf16 v[146:149], v[40:43], v[4:7], v[48:51]
	ds_read_b128 v[4:7], v108 offset:4608
	s_waitcnt lgkmcnt(0)
	v_mfma_f32_16x16x32_bf16 v[76:79], v[0:3], v[4:7], v[68:71]
	v_mfma_f32_16x16x32_bf16 v[72:75], v[24:27], v[4:7], v[72:75]
	v_mfma_f32_16x16x32_bf16 v[68:71], v[32:35], v[4:7], v[138:141]
	v_mfma_f32_16x16x32_bf16 v[52:55], v[40:43], v[4:7], v[64:67]
	v_mfma_f32_16x16x32_bf16 v[4:7], v[24:27], v[18:21], v[28:31]
	ds_read_b128 v[24:27], v109 offset:18496
	s_nop 0
	ds_read_b128 v[64:67], v108 offset:2368
	v_mfma_f32_16x16x32_bf16 v[8:11], v[0:3], v[18:21], v[14:17]
	v_mfma_f32_16x16x32_bf16 v[0:3], v[32:35], v[18:21], v[36:39]
	ds_read_b128 v[32:35], v109 offset:20800
	s_nop 1
	ds_read_b128 v[36:39], v108 offset:64
	v_mfma_f32_16x16x32_bf16 v[12:15], v[40:43], v[18:21], v[44:47]
	ds_read_b128 v[40:43], v109 offset:23104
	s_waitcnt lgkmcnt(1)
	v_mfma_f32_16x16x32_bf16 v[16:19], v[24:27], v[36:39], v[110:113]
	s_nop 2
	ds_read_b128 v[110:113], v108 offset:4672
	s_waitcnt lgkmcnt(0)
	v_mfma_f32_16x16x32_bf16 v[76:79], v[24:27], v[110:113], v[76:79]
	s_nop 1
	v_cvt_pk_bf16_f32 v16, v16, v17
	v_cvt_pk_bf16_f32 v17, v18, v19
	v_mfma_f32_16x16x32_bf16 v[72:75], v[32:35], v[110:113], v[72:75]
	v_mfma_f32_16x16x32_bf16 v[68:71], v[40:43], v[110:113], v[68:71]
	v_mfma_f32_16x16x32_bf16 v[52:55], v[56:59], v[110:113], v[52:55]
	ds_read_b128 v[110:113], v108 offset:6976
	v_mfma_f32_16x16x32_bf16 v[20:23], v[32:35], v[36:39], v[114:117]
	s_nop 2
	v_mov_b64_e32 v[114:115], s[84:85]
	v_or_b32_e32 v116, s2, v103
	v_mfma_f32_16x16x32_bf16 v[28:31], v[40:43], v[36:39], v[118:121]
	v_mad_i64_i32 v[100:101], s[2:3], v116, s8, v[114:115]
	v_or_b32_e32 v117, 16, v116
	v_mfma_f32_16x16x32_bf16 v[36:39], v[56:59], v[36:39], v[122:125]
	v_or_b32_e32 v120, 32, v116
	v_mad_i64_i32 v[118:119], s[2:3], v117, s8, v[114:115]
	s_nop 0
	v_or_b32_e32 v122, 48, v116
	v_or_b32_e32 v116, s0, v102
	v_mfma_f32_16x16x32_bf16 v[48:51], v[24:27], v[64:67], v[134:137]
	v_ashrrev_i32_e32 v117, 31, v116
	v_mad_i64_i32 v[120:121], s[2:3], v120, s8, v[114:115]
	v_mfma_f32_16x16x32_bf16 v[44:47], v[32:35], v[64:67], v[142:145]
	v_mad_i64_i32 v[114:115], s[2:3], v122, s8, v[114:115]
	v_cvt_pk_bf16_f32 v18, v20, v21
	v_mfma_f32_16x16x32_bf16 v[60:63], v[40:43], v[64:67], v[60:63]
	v_cvt_pk_bf16_f32 v19, v22, v23
	v_cvt_pk_bf16_f32 v20, v28, v29
	v_cvt_pk_bf16_f32 v21, v30, v31
	v_mfma_f32_16x16x32_bf16 v[64:67], v[56:59], v[64:67], v[146:149]
	v_cvt_pk_bf16_f32 v22, v36, v37
	v_cvt_pk_bf16_f32 v23, v38, v39
	v_cvt_pk_bf16_f32 v28, v48, v49
	s_waitcnt lgkmcnt(0)
	v_mfma_f32_16x16x32_bf16 v[8:11], v[24:27], v[110:113], v[8:11]
	v_lshlrev_b64 v[24:25], 1, v[116:117]
	v_lshl_add_u64 v[26:27], v[100:101], 0, v[24:25]
	v_lshl_add_u64 v[100:101], v[118:119], 0, v[24:25]
	v_mfma_f32_16x16x32_bf16 v[4:7], v[32:35], v[110:113], v[4:7]
	v_lshl_add_u64 v[32:33], v[120:121], 0, v[24:25]
	v_lshl_add_u64 v[24:25], v[114:115], 0, v[24:25]
	v_lshl_add_u64 v[26:27], v[26:27], 0, v[128:129]
	v_mfma_f32_16x16x32_bf16 v[0:3], v[40:43], v[110:113], v[0:3]
	v_lshl_add_u64 v[34:35], v[100:101], 0, v[128:129]
	v_lshl_add_u64 v[32:33], v[32:33], 0, v[128:129]
	v_lshl_add_u64 v[24:25], v[24:25], 0, v[128:129]
	v_mfma_f32_16x16x32_bf16 v[12:15], v[56:59], v[110:113], v[12:15]
	v_cvt_pk_bf16_f32 v29, v50, v51
	v_cvt_pk_bf16_f32 v30, v44, v45
	v_cvt_pk_bf16_f32 v31, v46, v47
	v_cvt_pk_bf16_f32 v36, v60, v61
	v_cvt_pk_bf16_f32 v37, v62, v63
	v_cvt_pk_bf16_f32 v38, v64, v65
	v_cvt_pk_bf16_f32 v39, v66, v67
	v_cvt_pk_bf16_f32 v40, v76, v77
	v_cvt_pk_bf16_f32 v41, v78, v79
	v_cvt_pk_bf16_f32 v42, v72, v73
	v_cvt_pk_bf16_f32 v43, v74, v75
	v_cvt_pk_bf16_f32 v44, v68, v69
	v_cvt_pk_bf16_f32 v45, v70, v71
	v_cvt_pk_bf16_f32 v46, v52, v53
	v_cvt_pk_bf16_f32 v47, v54, v55
	v_cvt_pk_bf16_f32 v8, v8, v9
	v_cvt_pk_bf16_f32 v9, v10, v11
	v_cvt_pk_bf16_f32 v4, v4, v5
	v_cvt_pk_bf16_f32 v5, v6, v7
	v_cvt_pk_bf16_f32 v0, v0, v1
	v_cvt_pk_bf16_f32 v1, v2, v3
	v_cvt_pk_bf16_f32 v2, v12, v13
	v_cvt_pk_bf16_f32 v3, v14, v15
	global_store_dwordx2 v[26:27], v[16:17], off
	global_store_dwordx2 v[26:27], v[18:19], off offset:32
	global_store_dwordx2 v[26:27], v[20:21], off offset:64
	global_store_dwordx2 v[26:27], v[22:23], off offset:96
	global_store_dwordx2 v[34:35], v[28:29], off
	global_store_dwordx2 v[34:35], v[30:31], off offset:32
	global_store_dwordx2 v[34:35], v[36:37], off offset:64
	global_store_dwordx2 v[34:35], v[38:39], off offset:96
	global_store_dwordx2 v[32:33], v[40:41], off
	global_store_dwordx2 v[32:33], v[42:43], off offset:32
	global_store_dwordx2 v[32:33], v[44:45], off offset:64
	global_store_dwordx2 v[32:33], v[46:47], off offset:96
	global_store_dwordx2 v[24:25], v[8:9], off
	global_store_dwordx2 v[24:25], v[4:5], off offset:32
	global_store_dwordx2 v[24:25], v[0:1], off offset:64
	global_store_dwordx2 v[24:25], v[2:3], off offset:96
	s_add_i32 s4, s1, s4
	s_cmpk_lt_i32 s4, 0x330
	s_cbranch_scc1 .LBB0_1296

.LBB0_1300:
	s_ashr_i32 s0, s10, 31
	s_lshr_b32 s0, s0, 30
	s_add_i32 s0, s10, s0
	s_ashr_i32 s11, s0, 2
	s_lshl_b32 s0, s11, 7
	s_ashr_i32 s1, s0, 31
	s_lshl_b64 s[6:7], s[0:1], 12
	s_lshl_b32 s1, s11, 9
	s_lshl_b32 s4, s10, 7
	s_sub_i32 s4, s4, s1
	s_ashr_i32 s5, s4, 31
	s_lshl_b64 s[12:13], s[4:5], 8
	s_add_u32 s8, s82, s6
	s_addc_u32 s9, s83, s7
	v_lshl_add_u64 v[54:55], s[8:9], 0, v[128:129]
	v_readlane_b32 s6, v252, 37
	s_waitcnt lgkmcnt(0)
	v_lshl_add_u64 v[18:19], v[54:55], 0, v[0:1]
	v_readlane_b32 s7, v252, 38
	s_add_u32 s6, s6, s12
	global_load_dwordx4 v[208:211], v[18:19], off offset:2208
	global_load_dwordx4 v[18:21], v[18:19], off offset:2080
	v_lshl_add_u64 v[42:43], v[54:55], 0, v[4:5]
	s_addc_u32 s7, s7, s13
	global_load_dwordx4 v[212:215], v[42:43], off offset:2208
	global_load_dwordx4 v[42:45], v[42:43], off offset:2080
	v_lshl_add_u64 v[50:51], v[54:55], 0, v[8:9]
	v_lshl_add_u64 v[62:63], s[6:7], 0, v[128:129]
	global_load_dwordx4 v[216:219], v[50:51], off offset:2208
	global_load_dwordx4 v[50:53], v[50:51], off offset:2080
	v_lshl_add_u64 v[54:55], v[54:55], 0, v[12:13]
	v_lshl_add_u64 v[38:39], v[62:63], 0, v[2:3]
	global_load_dwordx4 v[220:223], v[54:55], off offset:2208
	global_load_dwordx4 v[54:57], v[54:55], off offset:2080
	v_lshl_add_u64 v[46:47], v[62:63], 0, v[6:7]
	global_load_dwordx4 v[224:227], v[38:39], off offset:128
	global_load_dwordx4 v[38:41], v[38:39], off
	v_lshl_add_u64 v[58:59], v[62:63], 0, v[10:11]
	global_load_dwordx4 v[228:231], v[46:47], off offset:128
	global_load_dwordx4 v[46:49], v[46:47], off
	v_lshl_add_u64 v[62:63], v[62:63], 0, v[14:15]
	global_load_dwordx4 v[232:235], v[58:59], off offset:128
	global_load_dwordx4 v[58:61], v[58:59], off
	v_lshl_add_u64 v[126:127], s[8:9], 0, v[12:13]
	global_load_dwordx4 v[236:239], v[62:63], off offset:128
	global_load_dwordx4 v[62:65], v[62:63], off
	s_barrier
	v_lshl_add_u64 v[142:143], s[8:9], 0, v[0:1]
	v_lshl_add_u64 v[126:127], v[126:127], 0, v[128:129]
	v_lshl_add_u64 v[144:145], s[6:7], 0, v[2:3]
	v_lshl_add_u64 v[144:145], v[144:145], 0, v[128:129]
	v_or_b32_e32 v37, s0, v23
	v_mov_b32_e32 v17, v129
	s_waitcnt vmcnt(14)
	ds_write_b128 v31, v[18:21]
	s_waitcnt vmcnt(12)
	ds_write_b128 v32, v[42:45]
	s_waitcnt vmcnt(10)
	ds_write_b128 v33, v[50:53]
	s_waitcnt vmcnt(8)
	ds_write_b128 v34, v[54:57]
	s_waitcnt vmcnt(6)
	ds_write_b128 v31, v[38:41] offset:18432
	s_waitcnt vmcnt(4)
	ds_write_b128 v32, v[46:49] offset:18432
	s_waitcnt vmcnt(2)
	ds_write_b128 v33, v[58:61] offset:18432
	s_waitcnt vmcnt(0)
	ds_write_b128 v34, v[62:65] offset:18432
	s_waitcnt lgkmcnt(0)
	s_barrier
	ds_read_b128 v[18:21], v36 offset:18432
	ds_read_b128 v[38:41], v35
	ds_read_b128 v[42:45], v35 offset:64
	ds_read_b128 v[46:49], v36 offset:18496
	ds_read_b128 v[54:57], v36 offset:20736
	ds_read_b128 v[58:61], v36 offset:20800
	ds_read_b128 v[66:69], v36 offset:23040
	ds_read_b128 v[70:73], v36 offset:23104
	ds_read_b128 v[78:81], v36 offset:25344
	ds_read_b128 v[82:85], v36 offset:25408
	ds_read_b128 v[86:89], v35 offset:2304
	ds_read_b128 v[90:93], v35 offset:2368
	ds_read_b128 v[106:109], v35 offset:4608
	ds_read_b128 v[110:113], v35 offset:4672
	ds_read_b128 v[134:137], v35 offset:6912
	ds_read_b128 v[138:141], v35 offset:6976
	s_waitcnt lgkmcnt(14)
	v_mfma_f32_16x16x32_bf16 v[50:53], v[18:21], v[38:41], 0
	s_waitcnt lgkmcnt(11)
	v_mfma_f32_16x16x32_bf16 v[62:65], v[54:57], v[38:41], 0
	s_waitcnt lgkmcnt(9)
	v_mfma_f32_16x16x32_bf16 v[74:77], v[66:69], v[38:41], 0
	s_waitcnt lgkmcnt(7)
	v_mfma_f32_16x16x32_bf16 v[38:41], v[78:81], v[38:41], 0
	s_waitcnt lgkmcnt(5)
	v_mfma_f32_16x16x32_bf16 v[94:97], v[18:21], v[86:89], 0
	v_mfma_f32_16x16x32_bf16 v[98:101], v[54:57], v[86:89], 0
	v_mfma_f32_16x16x32_bf16 v[102:105], v[66:69], v[86:89], 0
	v_mfma_f32_16x16x32_bf16 v[86:89], v[78:81], v[86:89], 0
	s_waitcnt lgkmcnt(3)
	v_mfma_f32_16x16x32_bf16 v[114:117], v[18:21], v[106:109], 0
	v_mfma_f32_16x16x32_bf16 v[118:121], v[54:57], v[106:109], 0
	v_mfma_f32_16x16x32_bf16 v[122:125], v[66:69], v[106:109], 0
	v_mfma_f32_16x16x32_bf16 v[106:109], v[78:81], v[106:109], 0
	s_waitcnt lgkmcnt(1)
	v_mfma_f32_16x16x32_bf16 v[18:21], v[18:21], v[134:137], 0
	v_mfma_f32_16x16x32_bf16 v[54:57], v[54:57], v[134:137], 0
	v_mfma_f32_16x16x32_bf16 v[66:69], v[66:69], v[134:137], 0
	v_mfma_f32_16x16x32_bf16 v[78:81], v[78:81], v[134:137], 0
	v_lshl_add_u64 v[134:135], s[8:9], 0, v[8:9]
	v_lshl_add_u64 v[136:137], s[8:9], 0, v[4:5]
	v_lshl_add_u64 v[146:147], v[134:135], 0, v[128:129]
	v_mfma_f32_16x16x32_bf16 v[50:53], v[46:49], v[42:45], v[50:53]
	v_lshl_add_u64 v[134:135], v[136:137], 0, v[128:129]
	v_lshl_add_u64 v[136:137], s[6:7], 0, v[6:7]
	v_lshl_add_u64 v[148:149], v[136:137], 0, v[128:129]
	v_mfma_f32_16x16x32_bf16 v[62:65], v[58:61], v[42:45], v[62:65]
	v_mfma_f32_16x16x32_bf16 v[74:77], v[70:73], v[42:45], v[74:77]
	v_mfma_f32_16x16x32_bf16 v[38:41], v[82:85], v[42:45], v[38:41]
	v_mfma_f32_16x16x32_bf16 v[42:45], v[46:49], v[90:93], v[94:97]
	v_mfma_f32_16x16x32_bf16 v[94:97], v[58:61], v[90:93], v[98:101]
	v_mfma_f32_16x16x32_bf16 v[98:101], v[70:73], v[90:93], v[102:105]
	s_nop 2
	v_lshl_add_u64 v[102:103], s[6:7], 0, v[14:15]
	v_lshl_add_u64 v[104:105], s[6:7], 0, v[10:11]
	v_mfma_f32_16x16x32_bf16 v[86:89], v[82:85], v[90:93], v[86:89]
	v_lshl_add_u64 v[154:155], v[102:103], 0, v[128:129]
	v_lshl_add_u64 v[150:151], v[104:105], 0, v[128:129]
	v_mfma_f32_16x16x32_bf16 v[90:93], v[46:49], v[110:113], v[114:117]
	v_mfma_f32_16x16x32_bf16 v[102:105], v[58:61], v[110:113], v[118:121]
	s_nop 1
	v_lshl_add_u64 v[126:127], v[142:143], 0, v[128:129]
	s_nop 0
	v_mfma_f32_16x16x32_bf16 v[122:125], v[70:73], v[110:113], v[122:125]
	v_mfma_f32_16x16x32_bf16 v[106:109], v[82:85], v[110:113], v[106:109]
	s_nop 0
	s_nop 0
	s_waitcnt lgkmcnt(0)
	v_mfma_f32_16x16x32_bf16 v[18:21], v[46:49], v[138:141], v[18:21]
	s_barrier
	s_waitcnt vmcnt(5)
	ds_write_b128 v31, v[208:211]
	s_waitcnt vmcnt(4)
	ds_write_b128 v31, v[224:227] offset:18432
	ds_write_b128 v32, v[212:215]
	s_waitcnt vmcnt(3)
	ds_write_b128 v32, v[228:231] offset:18432
	s_waitcnt vmcnt(2)
	ds_write_b128 v33, v[216:219]
	s_waitcnt vmcnt(1)
	ds_write_b128 v33, v[232:235] offset:18432
	ds_write_b128 v34, v[220:223]
	s_waitcnt vmcnt(0)
	ds_write_b128 v34, v[236:239] offset:18432
	s_waitcnt lgkmcnt(0)
	s_barrier
	ds_read_b128 v[46:49], v36 offset:18432
	v_mfma_f32_16x16x32_bf16 v[54:57], v[58:61], v[138:141], v[54:57]
	v_mfma_f32_16x16x32_bf16 v[58:61], v[70:73], v[138:141], v[66:69]
	v_mfma_f32_16x16x32_bf16 v[66:69], v[82:85], v[138:141], v[78:81]
	ds_read_b128 v[70:73], v35
	s_nop 1
	ds_read_b128 v[78:81], v35 offset:64
	ds_read_b128 v[82:85], v36 offset:18496
	ds_read_b128 v[110:113], v36 offset:20736
	ds_read_b128 v[114:117], v36 offset:20800
	ds_read_b128 v[118:121], v36 offset:23040
	ds_read_b128 v[134:137], v36 offset:23104
	ds_read_b128 v[138:141], v36 offset:25344
	ds_read_b128 v[142:145], v36 offset:25408
	s_waitcnt lgkmcnt(8)
	v_mfma_f32_16x16x32_bf16 v[50:53], v[46:49], v[70:73], v[50:53]
	s_waitcnt lgkmcnt(5)
	v_mfma_f32_16x16x32_bf16 v[62:65], v[110:113], v[70:73], v[62:65]
	s_waitcnt lgkmcnt(3)
	v_mfma_f32_16x16x32_bf16 v[74:77], v[118:121], v[70:73], v[74:77]
	s_waitcnt lgkmcnt(1)
	v_mfma_f32_16x16x32_bf16 v[38:41], v[138:141], v[70:73], v[38:41]
	ds_read_b128 v[70:73], v35 offset:2304
	ds_read_b128 v[146:149], v35 offset:2368
	s_waitcnt lgkmcnt(1)
	v_mfma_f32_16x16x32_bf16 v[42:45], v[46:49], v[70:73], v[42:45]
	v_mfma_f32_16x16x32_bf16 v[94:97], v[110:113], v[70:73], v[94:97]
	v_mfma_f32_16x16x32_bf16 v[98:101], v[118:121], v[70:73], v[98:101]
	v_mfma_f32_16x16x32_bf16 v[70:73], v[138:141], v[70:73], v[86:89]
	s_nop 2
	ds_read_b128 v[86:89], v35 offset:4608
	ds_read_b128 v[150:153], v35 offset:4672
	ds_read_b128 v[154:157], v35 offset:6912
	s_waitcnt lgkmcnt(2)
	v_mfma_f32_16x16x32_bf16 v[90:93], v[46:49], v[86:89], v[90:93]
	v_mfma_f32_16x16x32_bf16 v[102:105], v[110:113], v[86:89], v[102:105]
	v_mfma_f32_16x16x32_bf16 v[122:125], v[118:121], v[86:89], v[122:125]
	v_mfma_f32_16x16x32_bf16 v[86:89], v[138:141], v[86:89], v[106:109]
	s_nop 2
	ds_read_b128 v[106:109], v35 offset:6976
	s_waitcnt lgkmcnt(1)
	v_mfma_f32_16x16x32_bf16 v[46:49], v[46:49], v[154:157], v[18:21]
	s_nop 2
	v_or_b32_e32 v20, v37, v22
	v_or_b32_e32 v18, s4, v24
	v_mfma_f32_16x16x32_bf16 v[50:53], v[82:85], v[78:81], v[50:53]
	v_ashrrev_i32_e32 v21, 31, v20
	v_ashrrev_i32_e32 v19, 31, v18
	v_lshlrev_b64 v[126:127], 10, v[20:21]
	v_lshlrev_b64 v[18:19], 1, v[18:19]
	v_lshl_add_u64 v[126:127], s[86:87], 0, v[126:127]
	v_mfma_f32_16x16x32_bf16 v[62:65], v[114:117], v[78:81], v[62:65]
	v_lshl_add_u64 v[126:127], v[126:127], 0, v[18:19]
	v_lshl_add_u64 v[126:127], v[126:127], 0, v[16:17]
	v_cvt_pk_bf16_f32 v50, v50, v51
	v_cvt_pk_bf16_f32 v51, v52, v53
	global_store_dwordx2 v[126:127], v[50:51], off
	v_lshlrev_b32_e32 v21, 16, v50
	v_and_b32_e32 v50, 0xffff0000, v50
	v_mul_f32_e32 v133, v50, v50
	v_mfma_f32_16x16x32_bf16 v[74:77], v[134:137], v[78:81], v[74:77]
	v_cvt_pk_bf16_f32 v158, v62, v63
	v_lshlrev_b32_e32 v62, 16, v51
	v_fmac_f32_e32 v133, v21, v21
	v_and_b32_e32 v63, 0xffff0000, v51
	v_fmac_f32_e32 v133, v62, v62
	v_cvt_pk_bf16_f32 v159, v64, v65
	v_lshlrev_b32_e32 v64, 16, v158
	v_fmac_f32_e32 v133, v63, v63
	v_and_b32_e32 v65, 0xffff0000, v158
	v_fmac_f32_e32 v133, v64, v64
	v_cvt_pk_bf16_f32 v160, v74, v75
	v_lshlrev_b32_e32 v74, 16, v159
	v_fmac_f32_e32 v133, v65, v65
	v_and_b32_e32 v75, 0xffff0000, v159
	v_fmac_f32_e32 v133, v74, v74
	v_mfma_f32_16x16x32_bf16 v[38:41], v[142:145], v[78:81], v[38:41]
	v_fmac_f32_e32 v133, v75, v75
	v_lshlrev_b32_e32 v21, 16, v160
	v_cvt_pk_bf16_f32 v161, v76, v77
	v_fmac_f32_e32 v133, v21, v21
	v_and_b32_e32 v21, 0xffff0000, v160
	v_mfma_f32_16x16x32_bf16 v[42:45], v[82:85], v[146:149], v[42:45]
	v_fmac_f32_e32 v133, v21, v21
	v_lshlrev_b32_e32 v21, 16, v161
	v_fmac_f32_e32 v133, v21, v21
	v_mfma_f32_16x16x32_bf16 v[50:53], v[110:113], v[154:157], v[54:57]
	v_and_b32_e32 v21, 0xffff0000, v161
	v_cvt_pk_bf16_f32 v38, v38, v39
	v_fmac_f32_e32 v133, v21, v21
	v_lshlrev_b32_e32 v21, 16, v38
	v_mfma_f32_16x16x32_bf16 v[54:57], v[118:121], v[154:157], v[58:61]
	v_cvt_pk_bf16_f32 v39, v40, v41
	v_fmac_f32_e32 v133, v21, v21
	v_and_b32_e32 v21, 0xffff0000, v38
	v_mfma_f32_16x16x32_bf16 v[58:61], v[138:141], v[154:157], v[66:69]
	v_cvt_pk_bf16_f32 v42, v42, v43
	v_fmac_f32_e32 v133, v21, v21
	v_lshlrev_b32_e32 v21, 16, v39
	v_mfma_f32_16x16x32_bf16 v[62:65], v[114:117], v[146:149], v[94:97]
	v_cvt_pk_bf16_f32 v43, v44, v45
	v_fmac_f32_e32 v133, v21, v21
	v_and_b32_e32 v21, 0xffff0000, v39
	s_waitcnt lgkmcnt(0)
	v_mfma_f32_16x16x32_bf16 v[44:47], v[82:85], v[106:109], v[46:49]
	global_store_dwordx2 v[126:127], v[158:159], off offset:32
	global_store_dwordx2 v[126:127], v[160:161], off offset:64
	global_store_dwordx2 v[126:127], v[38:39], off offset:96
	v_lshlrev_b32_e32 v39, 16, v42
	v_mfma_f32_16x16x32_bf16 v[48:51], v[114:117], v[106:109], v[50:53]
	v_or_b32_e32 v40, 16, v20
	v_ashrrev_i32_e32 v41, 31, v40
	v_lshlrev_b64 v[40:41], 10, v[40:41]
	v_and_b32_e32 v52, 0xffff0000, v42
	v_mfma_f32_16x16x32_bf16 v[74:77], v[82:85], v[150:153], v[90:93]
	v_mul_f32_e32 v82, v52, v52
	v_fmac_f32_e32 v82, v39, v39
	v_lshlrev_b32_e32 v39, 16, v43
	v_mfma_f32_16x16x32_bf16 v[66:69], v[134:137], v[146:149], v[98:101]
	v_fmac_f32_e32 v82, v39, v39
	v_and_b32_e32 v39, 0xffff0000, v43
	v_fmac_f32_e32 v82, v39, v39
	v_mfma_f32_16x16x32_bf16 v[52:55], v[134:137], v[106:109], v[54:57]
	v_lshl_add_u64 v[40:41], s[86:87], 0, v[40:41]
	v_lshl_add_u64 v[40:41], v[40:41], 0, v[18:19]
	v_lshl_add_u64 v[40:41], v[40:41], 0, v[16:17]
	v_mfma_f32_16x16x32_bf16 v[56:59], v[142:145], v[106:109], v[58:61]
	v_cvt_pk_bf16_f32 v44, v44, v45
	v_cvt_pk_bf16_f32 v45, v46, v47
	v_cvt_pk_bf16_f32 v46, v48, v49
	v_cvt_pk_bf16_f32 v60, v62, v63
	v_lshlrev_b32_e32 v39, 16, v60
	v_mfma_f32_16x16x32_bf16 v[70:73], v[142:145], v[146:149], v[70:73]
	v_cvt_pk_bf16_f32 v61, v64, v65
	v_fmac_f32_e32 v82, v39, v39
	v_and_b32_e32 v39, 0xffff0000, v60
	v_fmac_f32_e32 v82, v39, v39
	v_lshlrev_b32_e32 v39, 16, v61
	v_fmac_f32_e32 v82, v39, v39
	v_and_b32_e32 v39, 0xffff0000, v61
	v_cvt_pk_bf16_f32 v62, v66, v67
	v_fmac_f32_e32 v82, v39, v39
	v_lshlrev_b32_e32 v39, 16, v62
	v_cvt_pk_bf16_f32 v63, v68, v69
	v_fmac_f32_e32 v82, v39, v39
	v_and_b32_e32 v39, 0xffff0000, v62
	v_cvt_pk_bf16_f32 v64, v70, v71
	v_cvt_pk_bf16_f32 v65, v72, v73
	global_store_dwordx2 v[40:41], v[42:43], off
	global_store_dwordx2 v[40:41], v[60:61], off offset:32
	global_store_dwordx2 v[40:41], v[62:63], off offset:64
	global_store_dwordx2 v[40:41], v[64:65], off offset:96
	v_or_b32_e32 v42, 32, v20
	v_fmac_f32_e32 v82, v39, v39
	v_lshlrev_b32_e32 v39, 16, v63
	v_ashrrev_i32_e32 v43, 31, v42
	v_mfma_f32_16x16x32_bf16 v[78:81], v[114:117], v[150:153], v[102:105]
	v_fmac_f32_e32 v82, v39, v39
	v_and_b32_e32 v39, 0xffff0000, v63
	v_lshlrev_b64 v[42:43], 10, v[42:43]
	v_mfma_f32_16x16x32_bf16 v[90:93], v[134:137], v[150:153], v[122:125]
	v_fmac_f32_e32 v82, v39, v39
	v_lshlrev_b32_e32 v39, 16, v64
	v_lshl_add_u64 v[42:43], s[86:87], 0, v[42:43]
	v_mfma_f32_16x16x32_bf16 v[86:89], v[142:145], v[150:153], v[86:89]
	v_fmac_f32_e32 v82, v39, v39
	v_and_b32_e32 v39, 0xffff0000, v64
	v_cvt_pk_bf16_f32 v60, v74, v75
	v_lshl_add_u64 v[42:43], v[42:43], 0, v[18:19]
	v_fmac_f32_e32 v82, v39, v39
	v_lshlrev_b32_e32 v39, 16, v65
	v_cvt_pk_bf16_f32 v61, v76, v77
	v_lshl_add_u64 v[42:43], v[42:43], 0, v[16:17]
	v_and_b32_e32 v62, 0xffff0000, v60
	v_fmac_f32_e32 v82, v39, v39
	v_and_b32_e32 v39, 0xffff0000, v65
	v_mul_f32_e32 v68, v62, v62
	v_cvt_pk_bf16_f32 v62, v78, v79
	v_cvt_pk_bf16_f32 v63, v80, v81
	v_cvt_pk_bf16_f32 v64, v90, v91
	v_cvt_pk_bf16_f32 v65, v92, v93
	v_cvt_pk_bf16_f32 v66, v86, v87
	v_cvt_pk_bf16_f32 v67, v88, v89
	global_store_dwordx2 v[42:43], v[60:61], off
	global_store_dwordx2 v[42:43], v[62:63], off offset:32
	global_store_dwordx2 v[42:43], v[64:65], off offset:64
	global_store_dwordx2 v[42:43], v[66:67], off offset:96
	v_and_b32_e32 v43, 0xffff0000, v44
	v_lshlrev_b32_e32 v41, 16, v60
	v_or_b32_e32 v60, 48, v20
	v_lshlrev_b32_e32 v20, 16, v44
	v_mul_f32_e32 v43, v43, v43
	v_fmac_f32_e32 v68, v41, v41
	v_lshlrev_b32_e32 v41, 16, v61
	v_fmac_f32_e32 v43, v20, v20
	v_lshlrev_b32_e32 v20, 16, v45
	v_fmac_f32_e32 v68, v41, v41
	v_and_b32_e32 v41, 0xffff0000, v61
	v_fmac_f32_e32 v43, v20, v20
	v_and_b32_e32 v20, 0xffff0000, v45
	v_fmac_f32_e32 v68, v41, v41
	v_lshlrev_b32_e32 v41, 16, v62
	v_fmac_f32_e32 v43, v20, v20
	v_lshlrev_b32_e32 v20, 16, v46
	v_fmac_f32_e32 v68, v41, v41
	v_and_b32_e32 v41, 0xffff0000, v62
	v_cvt_pk_bf16_f32 v47, v50, v51
	v_fmac_f32_e32 v43, v20, v20
	v_and_b32_e32 v20, 0xffff0000, v46
	v_fmac_f32_e32 v68, v41, v41
	v_lshlrev_b32_e32 v41, 16, v63
	v_fmac_f32_e32 v43, v20, v20
	v_lshlrev_b32_e32 v20, 16, v47
	v_fmac_f32_e32 v68, v41, v41
	v_and_b32_e32 v41, 0xffff0000, v63
	v_fmac_f32_e32 v43, v20, v20
	v_and_b32_e32 v20, 0xffff0000, v47
	v_cvt_pk_bf16_f32 v48, v52, v53
	v_fmac_f32_e32 v68, v41, v41
	v_lshlrev_b32_e32 v41, 16, v64
	v_fmac_f32_e32 v43, v20, v20
	v_lshlrev_b32_e32 v20, 16, v48
	v_fmac_f32_e32 v68, v41, v41
	v_and_b32_e32 v41, 0xffff0000, v64
	v_cvt_pk_bf16_f32 v49, v54, v55
	v_fmac_f32_e32 v43, v20, v20
	v_and_b32_e32 v20, 0xffff0000, v48
	v_fmac_f32_e32 v68, v41, v41
	v_lshlrev_b32_e32 v41, 16, v65
	v_fmac_f32_e32 v43, v20, v20
	v_lshlrev_b32_e32 v20, 16, v49
	v_fmac_f32_e32 v68, v41, v41
	v_and_b32_e32 v41, 0xffff0000, v65
	v_fmac_f32_e32 v43, v20, v20
	v_and_b32_e32 v20, 0xffff0000, v49
	v_cvt_pk_bf16_f32 v50, v56, v57
	v_fmac_f32_e32 v68, v41, v41
	v_lshlrev_b32_e32 v41, 16, v66
	v_fmac_f32_e32 v43, v20, v20
	v_lshlrev_b32_e32 v20, 16, v50
	v_fmac_f32_e32 v68, v41, v41
	v_and_b32_e32 v41, 0xffff0000, v66
	v_cvt_pk_bf16_f32 v51, v58, v59
	v_fmac_f32_e32 v43, v20, v20
	v_and_b32_e32 v20, 0xffff0000, v50
	v_fmac_f32_e32 v68, v41, v41
	v_lshlrev_b32_e32 v41, 16, v67
	v_fmac_f32_e32 v43, v20, v20
	v_lshlrev_b32_e32 v20, 16, v51
	v_fmac_f32_e32 v68, v41, v41
	v_and_b32_e32 v41, 0xffff0000, v67
	v_fmac_f32_e32 v43, v20, v20
	v_and_b32_e32 v20, 0xffff0000, v51
	v_fmac_f32_e32 v133, v21, v21
	v_fmac_f32_e32 v82, v39, v39
	v_fmac_f32_e32 v68, v41, v41
	v_fmac_f32_e32 v43, v20, v20
	ds_bpermute_b32 v21, v25, v133
	ds_bpermute_b32 v39, v25, v82
	ds_bpermute_b32 v41, v25, v68
	ds_bpermute_b32 v20, v25, v43
	v_ashrrev_i32_e32 v61, 31, v60
	v_lshlrev_b64 v[52:53], 10, v[60:61]
	v_lshl_add_u64 v[52:53], s[86:87], 0, v[52:53]
	v_lshl_add_u64 v[18:19], v[52:53], 0, v[18:19]
	s_waitcnt lgkmcnt(3)
	v_add_f32_e32 v21, v133, v21
	s_waitcnt lgkmcnt(2)
	v_add_f32_e32 v39, v82, v39
	s_waitcnt lgkmcnt(1)
	v_add_f32_e32 v41, v68, v41
	v_lshl_add_u64 v[52:53], v[18:19], 0, v[16:17]
	s_waitcnt lgkmcnt(0)
	v_add_f32_e32 v17, v43, v20
	ds_bpermute_b32 v38, v26, v21
	ds_bpermute_b32 v40, v26, v39
	ds_bpermute_b32 v42, v26, v41
	ds_bpermute_b32 v18, v26, v17
	global_store_dwordx2 v[52:53], v[44:45], off
	global_store_dwordx2 v[52:53], v[46:47], off offset:32
	global_store_dwordx2 v[52:53], v[48:49], off offset:64
	global_store_dwordx2 v[52:53], v[50:51], off offset:96
	s_and_saveexec_b64 s[6:7], vcc
	s_cbranch_execz .LBB0_1299
	s_waitcnt lgkmcnt(3)
	v_add_f32_e32 v19, v21, v38
	s_waitcnt lgkmcnt(2)
	v_add_f32_e32 v20, v39, v40
	v_max3_f32 v19, v19, 0, v20
	s_waitcnt lgkmcnt(1)
	v_add_f32_e32 v20, v41, v42
	s_waitcnt lgkmcnt(0)
	v_add_f32_e32 v17, v17, v18
	v_max3_f32 v17, v19, v20, v17
	ds_bpermute_b32 v18, v27, v17
	s_waitcnt lgkmcnt(0)
	v_max_f32_e32 v18, v18, v18
	v_max_f32_e32 v17, v17, v18
	ds_bpermute_b32 v18, v28, v17
	s_waitcnt lgkmcnt(0)
	v_max_f32_e32 v18, v18, v18
	v_max_f32_e32 v17, v17, v18
	ds_bpermute_b32 v18, v29, v17
	s_waitcnt lgkmcnt(0)
	v_max_f32_e32 v18, v18, v18
	v_max_f32_e32 v17, v17, v18
	ds_bpermute_b32 v18, v30, v17
	s_and_b64 exec, exec, s[2:3]
	s_cbranch_execz .LBB0_1299
	s_addk_i32 s0, 0x8000
	s_waitcnt lgkmcnt(0)
	v_max_f32_e32 v18, v18, v18
	v_max_f32_e32 v17, v17, v17
	s_lshr_b32 s0, s0, 8
	v_max_f32_e32 v17, v17, v18
	s_ashr_i32 s1, s11, 5
	v_mov_b32_e32 v18, s0
	s_mov_b32 s0, 0x8000
	s_ashr_i32 s8, s4, 7
	v_mov_b32_e32 v19, s1
	v_cmp_gt_i32_e64 s[4:5], s0, v37
	s_ashr_i32 s9, s8, 31
	s_nop 0
	v_cndmask_b32_e64 v18, v18, v19, s[4:5]
	v_lshlrev_b32_e32 v18, 2, v18
	v_ashrrev_i32_e32 v19, 31, v18
	v_lshl_add_u64 v[18:19], v[18:19], 2, s[22:23]
	v_lshl_add_u64 v[18:19], s[8:9], 2, v[18:19]
	global_atomic_umax v[18:19], v17, off
	s_branch .LBB0_1299
